# attention work-queue: next-unit dequeue atomic issued at the start of each unit's final store block, counted vmcnt wait (no store drain at the dequeue)
# baseline (speedup 1.0000x reference)
.LBB0_954:
	v_writelane_b32 v255, s76, 8
	s_nop 1
	v_writelane_b32 v255, s77, 9
	v_writelane_b32 v255, s74, 10
	s_nop 1
	v_writelane_b32 v255, s75, 11
	v_writelane_b32 v255, s70, 12
	s_nop 1
	v_writelane_b32 v255, s71, 13
	v_writelane_b32 v255, s72, 14
	s_or_b64 exec, exec, s[0:1]
	v_readlane_b32 s0, v254, 44
	v_mov_b32_e32 v1, 0
	v_readlane_b32 s1, v254, 45
	s_waitcnt lgkmcnt(0)
	s_barrier
	s_mov_b64 s[82:83], 0x10000
	s_mov_b64 s[84:85], 0x2000
	s_nop 0
	global_load_dword v215, v1, s[0:1]
	v_readlane_b32 s0, v254, 8
	v_readlane_b32 s1, v254, 9
	s_mov_b64 s[4:5], s[0:1]
	s_add_u32 s0, s4, 0xf80000
	s_addc_u32 s1, s5, 0
	v_writelane_b32 v255, s0, 15
	v_readlane_b32 s2, v254, 10
	v_readlane_b32 s3, v254, 11
	v_writelane_b32 v255, s1, 16
	s_add_u32 s0, s4, 0xa000000
	v_writelane_b32 v255, s0, 17
	s_addc_u32 s0, s5, 0
	v_writelane_b32 v255, s0, 18
	s_lshl_b32 s0, s78, 6
	s_ashr_i32 s1, s0, 31
	s_lshl_b64 s[0:1], s[0:1], 2
	s_add_u32 s0, s4, s0
	s_addc_u32 s1, s5, s1
	v_writelane_b32 v255, s0, 19
	s_mov_b64 s[76:77], 0x20000
	s_mov_b32 s19, 0xff61b1e6
	v_writelane_b32 v255, s1, 20
	s_and_b64 s[0:1], s[96:97], exec
	s_cselect_b32 s0, 8, 64
	s_lshl_b32 s1, s69, 5
	v_writelane_b32 v255, s1, 21
	s_lshl_b32 s1, s69, 4
	v_writelane_b32 v255, s1, 22
	s_and_b32 s1, s1, 48
	v_writelane_b32 v255, s1, 23
	s_and_b32 s1, s69, 0x3fffffc
	v_writelane_b32 v255, s1, 24
	s_add_i32 s1, s69, 8
	s_lshl_b32 s2, s69, 10
	s_lshl_b32 s10, s0, 4
	s_and_b32 s1, s1, 0x7fffffc
	s_add_i32 s18, s2, 0
	v_readlane_b32 s2, v254, 18
	s_cmpk_lt_u32 s2, 0x100
	v_writelane_b32 v255, s1, 25
	s_cselect_b64 s[6:7], -1, 0
	s_add_i32 s2, s18, 0x2000
	v_writelane_b32 v255, s2, 26
	s_add_i32 s2, s18, 0x5400
	v_writelane_b32 v255, s2, 27
	s_lshl_b32 s2, s69, 13
	s_add_i32 s33, s18, 0x3400
	s_add_i32 s80, s18, 0x6800
	s_add_i32 s81, s18, 0x8800
	s_add_i32 s71, s18, 0xa800
	s_add_i32 s70, s18, 0xc800
	s_add_i32 s2, s2, 0
	v_writelane_b32 v255, s2, 28
	s_and_b64 s[2:3], s[96:97], exec
	s_cselect_b32 s2, 3, 6
	v_writelane_b32 v255, s2, 29
	s_add_i32 s0, s0, -1
	v_writelane_b32 v255, s0, 30
	s_add_u32 s0, s4, 0x13220000
	v_writelane_b32 v255, s0, 31
	s_addc_u32 s0, s5, 0
	v_writelane_b32 v255, s0, 32
	s_add_u32 s0, s4, 0x13210000
	v_writelane_b32 v255, s0, 33
	s_addc_u32 s0, s5, 0
	v_writelane_b32 v255, s0, 34
	v_writelane_b32 v255, s6, 35
	s_mov_b32 s1, 0
	s_mov_b64 s[74:75], 0x30000
	v_writelane_b32 v255, s7, 36
	v_cndmask_b32_e64 v216, 0, 1, s[6:7]
	v_mov_b32_e32 v217, 0x358637bd
	v_mov_b32_e32 v218, 0xf149f2ca
	v_mbcnt_hi_u32_b32 v214, -1, v210
	v_writelane_b32 v255, s10, 37
	v_mov_b32_e32 v249, 1
	v_mov_b32_e32 v250, 0
	s_cmp_lg_u32 s69, 0
	s_cbranch_scc1 .Lpf_setup_done
	v_readlane_b32 s98, v255, 19
	v_readlane_b32 s99, v255, 20
	s_mov_b64 exec, 1
	s_nop 3
	global_atomic_add v248, v250, v249, s[98:99] offset:64 sc0
	s_waitcnt vmcnt(0)
	s_mov_b64 exec, -1
.Lpf_setup_done:
	s_branch .LBB0_957

.LBB0_957:
	v_mbcnt_lo_u32_b32 v0, -1, 0
	v_mbcnt_hi_u32_b32 v0, -1, v0
	s_mov_b32 s0, 0x22000
	v_or_b32_e32 v219, s89, v0
	s_nop 0
	v_cmp_eq_u32_e32 vcc, 0, v219
	s_and_saveexec_b64 s[2:3], vcc
	s_cbranch_execz .LBB0_961
	s_mov_b64 s[6:7], exec
	v_mbcnt_lo_u32_b32 v0, s6, 0
	v_mbcnt_hi_u32_b32 v0, s7, v0
	v_cmp_eq_u32_e32 vcc, 0, v0
	s_and_saveexec_b64 s[4:5], vcc
	s_cbranch_execz .LBB0_960
	v_mov_b32_e32 v2, v248
.LBB0_960:
	s_or_b64 exec, exec, s[4:5]
	v_readfirstlane_b32 s4, v2
	s_nop 1
	v_add_u32_e32 v0, s4, v0
	s_cmp_lt_u32 s4, 32
	s_cbranch_scc1 .Lsplit_done
	s_cmp_lg_u32 s32, 0
	s_cbranch_scc1 .Lsplit_done
	v_readlane_b32 s6, v255, 19
	v_readlane_b32 s7, v255, 20
	s_nop 4

.LBB0_1025:
	s_or_b64 exec, exec, s[4:5]
	v_readlane_b32 s100, v254, 25
	s_cmp_lg_u32 s100, 0
	s_cbranch_scc1 .Lpf_skip_mla
	v_readlane_b32 s98, v255, 19
	v_readlane_b32 s99, v255, 20
	s_mov_b64 vcc, exec
	s_mov_b64 exec, 1
	s_nop 3
	global_atomic_add v248, v250, v249, s[98:99] offset:64 sc0
	s_mov_b64 exec, vcc
.Lpf_skip_mla:
	v_cvt_pk_bf16_f32 v2, v0, v2
	v_cvt_pk_bf16_f32 v3, v3, v4
	global_store_dwordx2 v[172:173], v[2:3], off
	v_cvt_pk_bf16_f32 v2, v5, v6
	v_cvt_pk_bf16_f32 v3, v7, v9
	global_store_dwordx2 v[172:173], v[2:3], off offset:16
	v_cvt_pk_bf16_f32 v2, v8, v10
	v_cvt_pk_bf16_f32 v3, v11, v13
	global_store_dwordx2 v[172:173], v[2:3], off offset:32
	v_cvt_pk_bf16_f32 v2, v12, v14
	v_cvt_pk_bf16_f32 v3, v15, v17
	global_store_dwordx2 v[172:173], v[2:3], off offset:48
	v_cvt_pk_bf16_f32 v2, v16, v50
	v_cvt_pk_bf16_f32 v3, v51, v53
	global_store_dwordx2 v[172:173], v[2:3], off offset:64
	v_cvt_pk_bf16_f32 v2, v52, v54
	v_cvt_pk_bf16_f32 v3, v55, v57
	global_store_dwordx2 v[172:173], v[2:3], off offset:80
	v_cvt_pk_bf16_f32 v2, v56, v58
	v_cvt_pk_bf16_f32 v3, v59, v61
	global_store_dwordx2 v[172:173], v[2:3], off offset:96
	v_cvt_pk_bf16_f32 v2, v60, v62
	v_cvt_pk_bf16_f32 v3, v63, v64
	global_store_dwordx2 v[172:173], v[2:3], off offset:112
	v_cvt_pk_bf16_f32 v2, v34, v35
	v_cvt_pk_bf16_f32 v3, v36, v65
	global_store_dwordx2 v[172:173], v[2:3], off offset:128
	v_cvt_pk_bf16_f32 v2, v37, v38
	v_cvt_pk_bf16_f32 v3, v39, v41
	global_store_dwordx2 v[172:173], v[2:3], off offset:144
	v_cvt_pk_bf16_f32 v2, v40, v42
	v_cvt_pk_bf16_f32 v3, v43, v45
	global_store_dwordx2 v[172:173], v[2:3], off offset:160
	v_cvt_pk_bf16_f32 v2, v44, v46
	v_cvt_pk_bf16_f32 v3, v47, v48
	global_store_dwordx2 v[172:173], v[2:3], off offset:176
	v_cvt_pk_bf16_f32 v2, v18, v19
	v_cvt_pk_bf16_f32 v3, v20, v49
	global_store_dwordx2 v[172:173], v[2:3], off offset:192
	v_cvt_pk_bf16_f32 v2, v21, v22
	v_cvt_pk_bf16_f32 v3, v23, v25
	global_store_dwordx2 v[172:173], v[2:3], off offset:208
	v_cvt_pk_bf16_f32 v2, v24, v26
	v_cvt_pk_bf16_f32 v3, v27, v29
	s_mov_b64 s[4:5], 0
	global_store_dwordx2 v[172:173], v[2:3], off offset:224
	v_cvt_pk_bf16_f32 v2, v28, v30
	v_cvt_pk_bf16_f32 v3, v31, v32
	global_store_dwordx2 v[172:173], v[2:3], off offset:240
	s_waitcnt vmcnt(12)

.LBB0_1080:
	ds_bpermute_b32 v0, v208, v183
	s_mov_b64 s[68:69], -1
	s_waitcnt lgkmcnt(0)
	v_add_f32_e32 v0, v183, v0
	v_div_scale_f32 v66, s[4:5], v0, v0, 1.0
	v_rcp_f32_e32 v67, v66
	s_nop 0
	v_fma_f32 v68, -v66, v67, 1.0
	v_fmac_f32_e32 v67, v68, v67
	v_div_scale_f32 v68, vcc, 1.0, v0, 1.0
	v_mul_f32_e32 v69, v68, v67
	v_fma_f32 v70, -v66, v69, v68
	v_fmac_f32_e32 v69, v70, v67
	v_fma_f32 v66, -v66, v69, v68
	v_div_fmas_f32 v66, v66, v67, v69
	v_div_fixup_f32 v66, v66, v0, 1.0
	s_and_b64 vcc, exec, s[92:93]
	s_cbranch_vccz .LBB0_1082
	v_readlane_b32 s100, v254, 25
	s_cmp_lg_u32 s100, 0
	s_cbranch_scc1 .Lpf_skip_dif
	v_readlane_b32 s98, v255, 19
	v_readlane_b32 s99, v255, 20
	s_mov_b64 vcc, exec
	s_mov_b64 exec, 1
	s_nop 3
	global_atomic_add v248, v250, v249, s[98:99] offset:64 sc0
	s_mov_b64 exec, vcc
.Lpf_skip_dif:
	ds_read2st64_b32 v[68:69], v204 offset0:240 offset1:241
	v_mul_f32_e32 v0, v215, v66
	ds_read2st64_b32 v[70:71], v204 offset0:242 offset1:243
	ds_read2st64_b32 v[72:73], v204 offset0:244 offset1:245
	ds_read2st64_b32 v[74:75], v204 offset0:246 offset1:247
	v_mov_b32_e32 v79, v28
	v_mov_b32_e32 v81, v32
	s_waitcnt lgkmcnt(3)
	v_lshlrev_b32_e32 v67, 16, v68
	v_and_b32_e32 v68, 0xffff0000, v68
	v_lshlrev_b32_e32 v76, 16, v69
	v_and_b32_e32 v69, 0xffff0000, v69
	v_fma_f32 v82, -v0, v3, v68
	v_fma_f32 v84, -v0, v5, v69
	v_fma_f32 v67, -v0, v2, v67
	v_mul_f32_e32 v68, v82, v82
	v_fma_f32 v83, -v0, v4, v76
	v_mul_f32_e32 v69, v84, v84
	v_fmac_f32_e32 v68, v67, v67
	v_fmac_f32_e32 v69, v83, v83
	v_add_f32_e32 v68, v68, v69
	s_waitcnt lgkmcnt(2)
	v_lshlrev_b32_e32 v69, 16, v70
	v_and_b32_e32 v70, 0xffff0000, v70
	v_fma_f32 v86, -v0, v7, v70
	v_fma_f32 v85, -v0, v6, v69
	v_mul_f32_e32 v69, v86, v86
	v_fmac_f32_e32 v69, v85, v85
	v_and_b32_e32 v70, 0xffff0000, v71
	v_add_f32_e32 v68, v68, v69
	v_lshlrev_b32_e32 v69, 16, v71
	v_fma_f32 v88, -v0, v9, v70
	v_fma_f32 v87, -v0, v8, v69
	v_mul_f32_e32 v69, v88, v88
	v_fmac_f32_e32 v69, v87, v87
	s_waitcnt lgkmcnt(1)
	v_and_b32_e32 v70, 0xffff0000, v72
	v_add_f32_e32 v68, v68, v69
	v_lshlrev_b32_e32 v69, 16, v72
	v_fma_f32 v90, -v0, v11, v70
	v_fma_f32 v89, -v0, v10, v69
	v_mul_f32_e32 v69, v90, v90
	v_fmac_f32_e32 v69, v89, v89
	v_and_b32_e32 v70, 0xffff0000, v73
	v_add_f32_e32 v68, v68, v69
	v_lshlrev_b32_e32 v69, 16, v73
	v_fma_f32 v92, -v0, v13, v70
	v_fma_f32 v91, -v0, v12, v69
	v_mul_f32_e32 v69, v92, v92
	v_fmac_f32_e32 v69, v91, v91
	s_waitcnt lgkmcnt(0)
	v_and_b32_e32 v70, 0xffff0000, v74
	v_add_f32_e32 v68, v68, v69
	v_lshlrev_b32_e32 v69, 16, v74
	v_fma_f32 v94, -v0, v15, v70
	v_fma_f32 v93, -v0, v14, v69
	v_mul_f32_e32 v69, v94, v94
	v_fmac_f32_e32 v69, v93, v93
	v_add_f32_e32 v70, v68, v69
	v_lshlrev_b32_e32 v68, 16, v75
	v_and_b32_e32 v69, 0xffff0000, v75
	v_fma_f32 v95, -v0, v16, v68
	v_fma_f32 v96, -v0, v17, v69
	ds_read2st64_b32 v[68:69], v204 offset0:248 offset1:249
	v_mul_f32_e32 v71, v96, v96
	v_fmac_f32_e32 v71, v95, v95
	v_add_f32_e32 v76, v70, v71
	ds_read2st64_b32 v[70:71], v204 offset0:250 offset1:251
	ds_read2st64_b32 v[72:73], v204 offset0:252 offset1:253
	ds_read2st64_b32 v[74:75], v204 offset0:254 offset1:255
	s_waitcnt lgkmcnt(3)
	v_lshlrev_b32_e32 v77, 16, v68
	v_and_b32_e32 v68, 0xffff0000, v68
	v_fma_f32 v98, -v0, v51, v68
	v_fma_f32 v97, -v0, v50, v77
	v_mul_f32_e32 v68, v98, v98
	v_fmac_f32_e32 v68, v97, v97
	v_add_f32_e32 v68, v76, v68
	v_lshlrev_b32_e32 v76, 16, v69
	v_and_b32_e32 v69, 0xffff0000, v69
	v_fma_f32 v100, -v0, v53, v69
	v_fma_f32 v99, -v0, v52, v76
	v_mul_f32_e32 v69, v100, v100
	v_fmac_f32_e32 v69, v99, v99
	v_add_f32_e32 v68, v68, v69
	s_waitcnt lgkmcnt(2)
	v_lshlrev_b32_e32 v69, 16, v70
	v_and_b32_e32 v70, 0xffff0000, v70
	v_fma_f32 v102, -v0, v55, v70
	v_fma_f32 v101, -v0, v54, v69
	v_mul_f32_e32 v69, v102, v102
	v_fmac_f32_e32 v69, v101, v101
	v_and_b32_e32 v70, 0xffff0000, v71
	v_add_f32_e32 v68, v68, v69
	v_lshlrev_b32_e32 v69, 16, v71
	v_fma_f32 v104, -v0, v57, v70
	v_fma_f32 v103, -v0, v56, v69
	v_mul_f32_e32 v69, v104, v104
	v_fmac_f32_e32 v69, v103, v103
	s_waitcnt lgkmcnt(1)
	v_and_b32_e32 v70, 0xffff0000, v72
	v_add_f32_e32 v68, v68, v69
	v_lshlrev_b32_e32 v69, 16, v72
	v_fma_f32 v106, -v0, v59, v70
	v_fma_f32 v105, -v0, v58, v69
	v_mul_f32_e32 v69, v106, v106
	v_fmac_f32_e32 v69, v105, v105
	v_and_b32_e32 v70, 0xffff0000, v73
	v_add_f32_e32 v68, v68, v69
	v_lshlrev_b32_e32 v69, 16, v73
	v_fma_f32 v108, -v0, v61, v70
	v_fma_f32 v107, -v0, v60, v69
	v_mul_f32_e32 v69, v108, v108
	v_fmac_f32_e32 v69, v107, v107
	s_waitcnt lgkmcnt(0)
	v_and_b32_e32 v70, 0xffff0000, v74
	v_add_f32_e32 v68, v68, v69
	v_lshlrev_b32_e32 v69, 16, v74
	v_fma_f32 v110, -v0, v63, v70
	v_fma_f32 v109, -v0, v62, v69
	v_mul_f32_e32 v69, v110, v110
	v_fmac_f32_e32 v69, v109, v109
	v_add_f32_e32 v70, v68, v69
	v_lshlrev_b32_e32 v68, 16, v75
	v_and_b32_e32 v69, 0xffff0000, v75
	v_fma_f32 v111, -v0, v64, v68
	v_fma_f32 v112, -v0, v65, v69
	ds_read2st64_b32 v[68:69], v205 offset0:16 offset1:17
	v_mul_f32_e32 v71, v112, v112
	v_fmac_f32_e32 v71, v111, v111
	v_add_f32_e32 v76, v70, v71
	ds_read2st64_b32 v[70:71], v205 offset0:18 offset1:19
	ds_read2st64_b32 v[72:73], v205 offset0:20 offset1:21
	ds_read2st64_b32 v[74:75], v205 offset0:22 offset1:23
	s_waitcnt lgkmcnt(3)
	v_lshlrev_b32_e32 v77, 16, v68
	v_and_b32_e32 v68, 0xffff0000, v68
	v_fma_f32 v114, -v0, v35, v68
	v_fma_f32 v113, -v0, v34, v77
	v_mul_f32_e32 v68, v114, v114
	v_fmac_f32_e32 v68, v113, v113
	v_add_f32_e32 v68, v76, v68
	v_lshlrev_b32_e32 v76, 16, v69
	v_and_b32_e32 v69, 0xffff0000, v69
	v_fma_f32 v116, -v0, v37, v69
	v_fma_f32 v115, -v0, v36, v76
	v_mul_f32_e32 v69, v116, v116
	v_fmac_f32_e32 v69, v115, v115
	v_add_f32_e32 v68, v68, v69
	s_waitcnt lgkmcnt(2)
	v_lshlrev_b32_e32 v69, 16, v70
	v_and_b32_e32 v70, 0xffff0000, v70
	v_fma_f32 v118, -v0, v39, v70
	v_fma_f32 v117, -v0, v38, v69
	v_mul_f32_e32 v69, v118, v118
	v_fmac_f32_e32 v69, v117, v117
	v_and_b32_e32 v70, 0xffff0000, v71
	v_add_f32_e32 v68, v68, v69
	v_lshlrev_b32_e32 v69, 16, v71
	v_fma_f32 v120, -v0, v41, v70
	v_fma_f32 v119, -v0, v40, v69
	v_mul_f32_e32 v69, v120, v120
	v_fmac_f32_e32 v69, v119, v119
	s_waitcnt lgkmcnt(1)
	v_and_b32_e32 v70, 0xffff0000, v72
	v_add_f32_e32 v68, v68, v69
	v_lshlrev_b32_e32 v69, 16, v72
	v_fma_f32 v122, -v0, v43, v70
	v_fma_f32 v121, -v0, v42, v69
	v_mul_f32_e32 v69, v122, v122
	v_fmac_f32_e32 v69, v121, v121
	v_and_b32_e32 v70, 0xffff0000, v73
	v_add_f32_e32 v68, v68, v69
	v_lshlrev_b32_e32 v69, 16, v73
	v_fma_f32 v124, -v0, v45, v70
	v_fma_f32 v123, -v0, v44, v69
	v_mul_f32_e32 v69, v124, v124
	v_fmac_f32_e32 v69, v123, v123
	s_waitcnt lgkmcnt(0)
	v_and_b32_e32 v70, 0xffff0000, v74
	v_add_f32_e32 v68, v68, v69
	v_lshlrev_b32_e32 v69, 16, v74
	v_fma_f32 v126, -v0, v47, v70
	v_fma_f32 v125, -v0, v46, v69
	v_mul_f32_e32 v69, v126, v126
	v_fmac_f32_e32 v69, v125, v125
	v_add_f32_e32 v70, v68, v69
	v_lshlrev_b32_e32 v68, 16, v75
	v_and_b32_e32 v69, 0xffff0000, v75
	v_fma_f32 v127, -v0, v48, v68
	v_fma_f32 v128, -v0, v49, v69
	ds_read2st64_b32 v[68:69], v205 offset0:24 offset1:25
	v_mul_f32_e32 v71, v128, v128
	v_fmac_f32_e32 v71, v127, v127
	v_add_f32_e32 v76, v70, v71
	ds_read2st64_b32 v[70:71], v205 offset0:26 offset1:27
	ds_read2st64_b32 v[72:73], v205 offset0:28 offset1:29
	ds_read2st64_b32 v[74:75], v205 offset0:30 offset1:31
	s_waitcnt lgkmcnt(3)
	v_lshlrev_b32_e32 v77, 16, v68
	v_and_b32_e32 v68, 0xffff0000, v68
	v_fma_f32 v130, -v0, v19, v68
	v_fma_f32 v129, -v0, v18, v77
	v_mul_f32_e32 v68, v130, v130
	v_fmac_f32_e32 v68, v129, v129
	v_add_f32_e32 v68, v76, v68
	v_lshlrev_b32_e32 v76, 16, v69
	v_and_b32_e32 v69, 0xffff0000, v69
	v_fma_f32 v132, -v0, v21, v69
	v_fma_f32 v131, -v0, v20, v76
	v_mul_f32_e32 v69, v132, v132
	v_fmac_f32_e32 v69, v131, v131
	v_add_f32_e32 v78, v68, v69
	s_waitcnt lgkmcnt(2)
	v_lshlrev_b32_e32 v69, 16, v71
	v_lshlrev_b32_e32 v68, 16, v70
	v_mov_b32_e32 v76, v22
	v_mov_b32_e32 v77, v24
	v_and_b32_e32 v71, 0xffff0000, v71
	v_and_b32_e32 v70, 0xffff0000, v70
	v_pk_fma_f32 v[68:69], v[0:1], v[76:77], v[68:69] op_sel_hi:[0,1,1] neg_lo:[1,0,0] neg_hi:[1,0,0]
	v_mov_b32_e32 v76, v23
	v_mov_b32_e32 v77, v25
	v_pk_fma_f32 v[70:71], v[0:1], v[76:77], v[70:71] op_sel_hi:[0,1,1] neg_lo:[1,0,0] neg_hi:[1,0,0]
	v_pk_mul_f32 v[76:77], v[70:71], v[70:71]
	s_nop 0
	v_pk_fma_f32 v[76:77], v[68:69], v[68:69], v[76:77]
	s_nop 0
	v_add_f32_e32 v76, v78, v76
	v_add_f32_e32 v80, v76, v77
	s_waitcnt lgkmcnt(1)
	v_lshlrev_b32_e32 v77, 16, v73
	v_lshlrev_b32_e32 v76, 16, v72
	v_mov_b32_e32 v78, v26
	v_and_b32_e32 v73, 0xffff0000, v73
	v_and_b32_e32 v72, 0xffff0000, v72
	v_pk_fma_f32 v[76:77], v[0:1], v[78:79], v[76:77] op_sel_hi:[0,1,1] neg_lo:[1,0,0] neg_hi:[1,0,0]
	v_mov_b32_e32 v78, v27
	v_mov_b32_e32 v79, v29
	v_pk_fma_f32 v[72:73], v[0:1], v[78:79], v[72:73] op_sel_hi:[0,1,1] neg_lo:[1,0,0] neg_hi:[1,0,0]
	v_pk_mul_f32 v[78:79], v[72:73], v[72:73]
	s_nop 0
	v_pk_fma_f32 v[78:79], v[76:77], v[76:77], v[78:79]
	s_nop 0
	v_add_f32_e32 v78, v80, v78
	v_add_f32_e32 v133, v78, v79
	s_waitcnt lgkmcnt(0)
	v_lshlrev_b32_e32 v79, 16, v75
	v_lshlrev_b32_e32 v78, 16, v74
	v_mov_b32_e32 v80, v30
	v_and_b32_e32 v75, 0xffff0000, v75
	v_and_b32_e32 v74, 0xffff0000, v74
	v_pk_fma_f32 v[78:79], v[0:1], v[80:81], v[78:79] op_sel_hi:[0,1,1] neg_lo:[1,0,0] neg_hi:[1,0,0]
	v_mov_b32_e32 v80, v31
	v_mov_b32_e32 v81, v33
	v_pk_fma_f32 v[74:75], v[0:1], v[80:81], v[74:75] op_sel_hi:[0,1,1] neg_lo:[1,0,0] neg_hi:[1,0,0]
	v_pk_mul_f32 v[80:81], v[74:75], v[74:75]
	s_nop 0
	v_pk_fma_f32 v[80:81], v[78:79], v[78:79], v[80:81]
	s_nop 0
	v_add_f32_e32 v0, v133, v80
	v_add_f32_e32 v0, v0, v81
	ds_bpermute_b32 v80, v208, v0
	s_waitcnt lgkmcnt(0)
	v_add_f32_e32 v0, v0, v80
	v_fmamk_f32 v0, v0, 0x3c000000, v217
	v_rsq_f32_e32 v0, v0
	s_nop 0
	v_mul_f32_e32 v67, v0, v67
	v_mul_f32_e32 v80, v0, v82
	v_cvt_pk_bf16_f32 v80, v67, v80
	v_mul_f32_e32 v67, v0, v83
	v_mul_f32_e32 v81, v0, v84
	v_cvt_pk_bf16_f32 v81, v67, v81
	global_store_dwordx2 v[172:173], v[80:81], off
	v_mul_f32_e32 v67, v0, v85
	v_mul_f32_e32 v80, v0, v86
	v_cvt_pk_bf16_f32 v80, v67, v80
	v_mul_f32_e32 v67, v0, v87
	v_mul_f32_e32 v81, v0, v88
	v_cvt_pk_bf16_f32 v81, v67, v81
	global_store_dwordx2 v[172:173], v[80:81], off offset:16
	v_mul_f32_e32 v67, v0, v89
	v_mul_f32_e32 v80, v0, v90
	v_cvt_pk_bf16_f32 v80, v67, v80
	v_mul_f32_e32 v67, v0, v91
	v_mul_f32_e32 v81, v0, v92
	v_cvt_pk_bf16_f32 v81, v67, v81
	global_store_dwordx2 v[172:173], v[80:81], off offset:32
	v_mul_f32_e32 v67, v0, v93
	v_mul_f32_e32 v80, v0, v94
	v_cvt_pk_bf16_f32 v80, v67, v80
	v_mul_f32_e32 v67, v0, v95
	v_mul_f32_e32 v81, v0, v96
	v_cvt_pk_bf16_f32 v81, v67, v81
	global_store_dwordx2 v[172:173], v[80:81], off offset:48
	v_mul_f32_e32 v67, v0, v97
	v_mul_f32_e32 v80, v0, v98
	v_cvt_pk_bf16_f32 v80, v67, v80
	v_mul_f32_e32 v67, v0, v99
	v_mul_f32_e32 v81, v0, v100
	v_cvt_pk_bf16_f32 v81, v67, v81
	global_store_dwordx2 v[172:173], v[80:81], off offset:64
	v_mul_f32_e32 v67, v0, v101
	v_mul_f32_e32 v80, v0, v102
	v_cvt_pk_bf16_f32 v80, v67, v80
	v_mul_f32_e32 v67, v0, v103
	v_mul_f32_e32 v81, v0, v104
	v_cvt_pk_bf16_f32 v81, v67, v81
	global_store_dwordx2 v[172:173], v[80:81], off offset:80
	v_mul_f32_e32 v67, v0, v105
	v_mul_f32_e32 v80, v0, v106
	v_cvt_pk_bf16_f32 v80, v67, v80
	v_mul_f32_e32 v67, v0, v107
	v_mul_f32_e32 v81, v0, v108
	v_cvt_pk_bf16_f32 v81, v67, v81
	global_store_dwordx2 v[172:173], v[80:81], off offset:96
	v_mul_f32_e32 v67, v0, v109
	v_mul_f32_e32 v80, v0, v110
	v_cvt_pk_bf16_f32 v80, v67, v80
	v_mul_f32_e32 v67, v0, v111
	v_mul_f32_e32 v81, v0, v112
	v_cvt_pk_bf16_f32 v81, v67, v81
	global_store_dwordx2 v[172:173], v[80:81], off offset:112
	v_mul_f32_e32 v67, v0, v113
	v_mul_f32_e32 v80, v0, v114
	v_cvt_pk_bf16_f32 v80, v67, v80
	v_mul_f32_e32 v67, v0, v115
	v_mul_f32_e32 v81, v0, v116
	v_cvt_pk_bf16_f32 v81, v67, v81
	global_store_dwordx2 v[172:173], v[80:81], off offset:128
	v_mul_f32_e32 v67, v0, v117
	v_mul_f32_e32 v80, v0, v118
	v_cvt_pk_bf16_f32 v80, v67, v80
	v_mul_f32_e32 v67, v0, v119
	v_mul_f32_e32 v81, v0, v120
	v_cvt_pk_bf16_f32 v81, v67, v81
	global_store_dwordx2 v[172:173], v[80:81], off offset:144
	v_mul_f32_e32 v67, v0, v121
	v_mul_f32_e32 v80, v0, v122
	v_cvt_pk_bf16_f32 v80, v67, v80
	v_mul_f32_e32 v67, v0, v123
	v_mul_f32_e32 v81, v0, v124
	v_cvt_pk_bf16_f32 v81, v67, v81
	global_store_dwordx2 v[172:173], v[80:81], off offset:160
	v_mul_f32_e32 v67, v0, v125
	v_mul_f32_e32 v80, v0, v126
	v_cvt_pk_bf16_f32 v80, v67, v80
	v_mul_f32_e32 v67, v0, v127
	v_mul_f32_e32 v81, v0, v128
	v_cvt_pk_bf16_f32 v81, v67, v81
	global_store_dwordx2 v[172:173], v[80:81], off offset:176
	v_mul_f32_e32 v67, v0, v129
	v_mul_f32_e32 v80, v0, v130
	v_cvt_pk_bf16_f32 v80, v67, v80
	v_mul_f32_e32 v67, v0, v131
	v_mul_f32_e32 v81, v0, v132
	v_cvt_pk_bf16_f32 v81, v67, v81
	v_mul_f32_e32 v67, v0, v68
	v_mul_f32_e32 v68, v0, v70
	global_store_dwordx2 v[172:173], v[80:81], off offset:192
	v_cvt_pk_bf16_f32 v68, v67, v68
	v_mul_f32_e32 v67, v0, v69
	v_mul_f32_e32 v69, v0, v71
	v_cvt_pk_bf16_f32 v69, v67, v69
	global_store_dwordx2 v[172:173], v[68:69], off offset:208
	v_mul_f32_e32 v67, v0, v76
	v_mul_f32_e32 v68, v0, v72
	v_cvt_pk_bf16_f32 v68, v67, v68
	v_mul_f32_e32 v67, v0, v77
	v_mul_f32_e32 v69, v0, v73
	v_cvt_pk_bf16_f32 v69, v67, v69
	global_store_dwordx2 v[172:173], v[68:69], off offset:224
	v_mul_f32_e32 v67, v0, v78
	v_mul_f32_e32 v68, v0, v74
	v_cvt_pk_bf16_f32 v68, v67, v68
	v_mul_f32_e32 v67, v0, v79
	v_mul_f32_e32 v0, v0, v75
	v_cvt_pk_bf16_f32 v69, v67, v0
	global_store_dwordx2 v[172:173], v[68:69], off offset:240
	s_waitcnt vmcnt(12)
	s_cbranch_execnz .LBB0_1028
	s_branch .LBB0_1083
